# attention: software-pipelined LDS fragment reads in QK^T and PV (7-8 buffers, counted lgkmcnt)
# speedup vs baseline: 1.0235x; 1.0235x over previous
.LBB0_969:
	s_xor_b32 s60, s29, 2
	s_and_b32 s64, s60, 3
	s_mul_i32 s64, s64, 0x8c00
	v_add_u32_e32 v216, s64, v224
	v_mov_b64_e32 v[150:151], s[50:51]
	v_mov_b64_e32 v[148:149], s[48:49]
	s_add_i32 s42, s60, s12
	s_and_b32 s42, s42, 3
	s_mul_i32 s42, s42, 0x8c00
	v_add_u32_e32 v217, s42, v225
	s_add_i32 s42, s60, s13
	s_and_b32 s42, s42, 3
	s_mul_i32 s42, s42, 0x8c00
	v_add_u32_e32 v236, s42, v226
	s_add_i32 s42, s60, 1
	s_and_b32 s61, s42, 3
	s_mul_i32 s61, s61, 0x8c00
	v_add_u32_e32 v237, s61, v224
	s_add_i32 s42, s60, s14
	s_and_b32 s42, s42, 3
	s_mul_i32 s42, s42, 0x8c00
	v_add_u32_e32 v250, s42, v227
	s_add_i32 s42, s60, s15
	s_and_b32 s42, s42, 3
	s_mul_i32 s42, s42, 0x8c00
	v_add_u32_e32 v251, s42, v228
	v_add_u32_e32 v252, s27, v224
	s_andn2_b64 vcc, exec, s[46:47]
	v_cndmask_b32_e64 v167, 0, 1, s[46:47]
	v_cmp_ne_u32_e64 s[42:43], 1, v167
	ds_read_b128 v[188:191], v216
	ds_read_b128 v[192:195], v216 offset:64
	ds_read_b128 v[196:199], v216 offset:128
	ds_read_b128 v[200:203], v216 offset:192
	ds_read_b128 v[204:207], v216 offset:4352
	ds_read_b128 v[208:211], v216 offset:4416
	ds_read_b128 v[212:215], v216 offset:4480
	s_waitcnt lgkmcnt(6)
	v_mfma_f32_16x16x32_bf16 v[84:87], v[188:191], v[64:67], v[148:151]
	ds_read_b128 v[246:249], v216 offset:4544
	s_waitcnt lgkmcnt(6)
	v_mfma_f32_16x16x32_bf16 v[84:87], v[192:195], v[52:55], v[84:87]
	ds_read_b128 v[188:191], v217
	s_waitcnt lgkmcnt(6)
	v_mfma_f32_16x16x32_bf16 v[84:87], v[196:199], v[56:59], v[84:87]
	ds_read_b128 v[192:195], v217 offset:64
	s_waitcnt lgkmcnt(6)
	v_mfma_f32_16x16x32_bf16 v[140:143], v[200:203], v[60:63], v[84:87]
	ds_read_b128 v[196:199], v217 offset:128
	s_waitcnt lgkmcnt(6)
	v_mfma_f32_16x16x32_bf16 v[88:91], v[204:207], v[64:67], v[148:151]
	v_mfma_f32_16x16x32_bf16 v[84:87], v[204:207], v[68:71], v[148:151]
	ds_read_b128 v[200:203], v217 offset:192
	s_waitcnt lgkmcnt(6)
	v_mfma_f32_16x16x32_bf16 v[88:91], v[208:211], v[52:55], v[88:91]
	v_mfma_f32_16x16x32_bf16 v[84:87], v[208:211], v[72:75], v[84:87]
	ds_read_b128 v[204:207], v236
	s_waitcnt lgkmcnt(6)
	v_mfma_f32_16x16x32_bf16 v[88:91], v[212:215], v[56:59], v[88:91]
	v_mfma_f32_16x16x32_bf16 v[92:95], v[212:215], v[76:79], v[84:87]
	ds_read_b128 v[208:211], v236 offset:64
	s_waitcnt lgkmcnt(6)
	v_mfma_f32_16x16x32_bf16 v[84:87], v[246:249], v[60:63], v[88:91]
	v_mfma_f32_16x16x32_bf16 v[144:147], v[246:249], v[80:83], v[92:95]
	ds_read_b128 v[212:215], v236 offset:128
	s_waitcnt lgkmcnt(6)
	v_mfma_f32_16x16x32_bf16 v[92:95], v[188:191], v[64:67], v[148:151]
	v_mfma_f32_16x16x32_bf16 v[88:91], v[188:191], v[68:71], v[148:151]
	ds_read_b128 v[246:249], v236 offset:192
	s_waitcnt lgkmcnt(6)
	v_mfma_f32_16x16x32_bf16 v[92:95], v[192:195], v[52:55], v[92:95]
	v_mfma_f32_16x16x32_bf16 v[88:91], v[192:195], v[72:75], v[88:91]
	ds_read_b128 v[188:191], v237
	s_waitcnt lgkmcnt(6)
	v_mfma_f32_16x16x32_bf16 v[92:95], v[196:199], v[56:59], v[92:95]
	v_mfma_f32_16x16x32_bf16 v[88:91], v[196:199], v[76:79], v[88:91]
	ds_read_b128 v[192:195], v237 offset:64
	s_waitcnt lgkmcnt(6)
	v_mfma_f32_16x16x32_bf16 v[92:95], v[200:203], v[60:63], v[92:95]
	v_mfma_f32_16x16x32_bf16 v[88:91], v[200:203], v[80:83], v[88:91]
	ds_read_b128 v[196:199], v237 offset:128
	s_waitcnt lgkmcnt(6)
	v_mfma_f32_16x16x32_bf16 v[100:103], v[204:207], v[64:67], v[148:151]
	v_mfma_f32_16x16x32_bf16 v[96:99], v[204:207], v[68:71], v[148:151]
	ds_read_b128 v[200:203], v237 offset:192
	s_waitcnt lgkmcnt(6)
	v_mfma_f32_16x16x32_bf16 v[100:103], v[208:211], v[52:55], v[100:103]
	v_mfma_f32_16x16x32_bf16 v[96:99], v[208:211], v[72:75], v[96:99]
	ds_read_b128 v[204:207], v237 offset:4352
	s_waitcnt lgkmcnt(6)
	v_mfma_f32_16x16x32_bf16 v[100:103], v[212:215], v[56:59], v[100:103]
	v_mfma_f32_16x16x32_bf16 v[96:99], v[212:215], v[76:79], v[96:99]
	ds_read_b128 v[208:211], v237 offset:4416
	s_waitcnt lgkmcnt(6)
	v_mfma_f32_16x16x32_bf16 v[100:103], v[246:249], v[60:63], v[100:103]
	v_mfma_f32_16x16x32_bf16 v[96:99], v[246:249], v[80:83], v[96:99]
	ds_read_b128 v[212:215], v237 offset:4480
	s_waitcnt lgkmcnt(6)
	v_mfma_f32_16x16x32_bf16 v[108:111], v[188:191], v[64:67], v[148:151]
	v_mfma_f32_16x16x32_bf16 v[104:107], v[188:191], v[68:71], v[148:151]
	ds_read_b128 v[246:249], v237 offset:4544
	s_waitcnt lgkmcnt(6)
	v_mfma_f32_16x16x32_bf16 v[108:111], v[192:195], v[52:55], v[108:111]
	v_mfma_f32_16x16x32_bf16 v[104:107], v[192:195], v[72:75], v[104:107]
	ds_read_b128 v[188:191], v250
	s_waitcnt lgkmcnt(6)
	v_mfma_f32_16x16x32_bf16 v[108:111], v[196:199], v[56:59], v[108:111]
	v_mfma_f32_16x16x32_bf16 v[104:107], v[196:199], v[76:79], v[104:107]
	ds_read_b128 v[192:195], v250 offset:64
	s_waitcnt lgkmcnt(6)
	v_mfma_f32_16x16x32_bf16 v[108:111], v[200:203], v[60:63], v[108:111]
	v_mfma_f32_16x16x32_bf16 v[104:107], v[200:203], v[80:83], v[104:107]
	ds_read_b128 v[196:199], v250 offset:128
	s_waitcnt lgkmcnt(6)
	v_mfma_f32_16x16x32_bf16 v[116:119], v[204:207], v[64:67], v[148:151]
	v_mfma_f32_16x16x32_bf16 v[112:115], v[204:207], v[68:71], v[148:151]
	ds_read_b128 v[200:203], v250 offset:192
	s_waitcnt lgkmcnt(6)
	v_mfma_f32_16x16x32_bf16 v[116:119], v[208:211], v[52:55], v[116:119]
	v_mfma_f32_16x16x32_bf16 v[112:115], v[208:211], v[72:75], v[112:115]
	ds_read_b128 v[204:207], v251
	s_waitcnt lgkmcnt(6)
	v_mfma_f32_16x16x32_bf16 v[116:119], v[212:215], v[56:59], v[116:119]
	v_mfma_f32_16x16x32_bf16 v[112:115], v[212:215], v[76:79], v[112:115]
	ds_read_b128 v[208:211], v251 offset:64
	s_waitcnt lgkmcnt(6)
	v_mfma_f32_16x16x32_bf16 v[116:119], v[246:249], v[60:63], v[116:119]
	v_mfma_f32_16x16x32_bf16 v[112:115], v[246:249], v[80:83], v[112:115]
	ds_read_b128 v[212:215], v251 offset:128
	s_waitcnt lgkmcnt(6)
	v_mfma_f32_16x16x32_bf16 v[124:127], v[188:191], v[64:67], v[148:151]
	v_mfma_f32_16x16x32_bf16 v[120:123], v[188:191], v[68:71], v[148:151]
	ds_read_b128 v[246:249], v251 offset:192
	s_waitcnt lgkmcnt(6)
	v_mfma_f32_16x16x32_bf16 v[124:127], v[192:195], v[52:55], v[124:127]
	v_mfma_f32_16x16x32_bf16 v[120:123], v[192:195], v[72:75], v[120:123]
	ds_read_b128 v[188:191], v252
	s_waitcnt lgkmcnt(6)
	v_mfma_f32_16x16x32_bf16 v[124:127], v[196:199], v[56:59], v[124:127]
	v_mfma_f32_16x16x32_bf16 v[120:123], v[196:199], v[76:79], v[120:123]
	ds_read_b128 v[192:195], v252 offset:64
	s_waitcnt lgkmcnt(6)
	v_mfma_f32_16x16x32_bf16 v[124:127], v[200:203], v[60:63], v[124:127]
	v_mfma_f32_16x16x32_bf16 v[120:123], v[200:203], v[80:83], v[120:123]
	ds_read_b128 v[196:199], v252 offset:128
	s_waitcnt lgkmcnt(6)
	v_mfma_f32_16x16x32_bf16 v[132:135], v[204:207], v[64:67], v[148:151]
	v_mfma_f32_16x16x32_bf16 v[128:131], v[204:207], v[68:71], v[148:151]
	ds_read_b128 v[200:203], v252 offset:192
	s_waitcnt lgkmcnt(6)
	v_mfma_f32_16x16x32_bf16 v[132:135], v[208:211], v[52:55], v[132:135]
	v_mfma_f32_16x16x32_bf16 v[128:131], v[208:211], v[72:75], v[128:131]
	ds_read_b128 v[204:207], v252 offset:4352
	s_waitcnt lgkmcnt(6)
	v_mfma_f32_16x16x32_bf16 v[132:135], v[212:215], v[56:59], v[132:135]
	v_mfma_f32_16x16x32_bf16 v[128:131], v[212:215], v[76:79], v[128:131]
	ds_read_b128 v[208:211], v252 offset:4416
	s_waitcnt lgkmcnt(6)
	v_mfma_f32_16x16x32_bf16 v[132:135], v[246:249], v[60:63], v[132:135]
	v_mfma_f32_16x16x32_bf16 v[128:131], v[246:249], v[80:83], v[128:131]
	ds_read_b128 v[212:215], v252 offset:4480
	s_waitcnt lgkmcnt(6)
	v_mfma_f32_16x16x32_bf16 v[152:155], v[188:191], v[64:67], v[148:151]
	v_mfma_f32_16x16x32_bf16 v[136:139], v[188:191], v[68:71], v[148:151]
	ds_read_b128 v[246:249], v252 offset:4544
	s_waitcnt lgkmcnt(6)
	v_mfma_f32_16x16x32_bf16 v[152:155], v[192:195], v[52:55], v[152:155]
	v_mfma_f32_16x16x32_bf16 v[136:139], v[192:195], v[72:75], v[136:139]
	s_waitcnt lgkmcnt(5)
	v_mfma_f32_16x16x32_bf16 v[152:155], v[196:199], v[56:59], v[152:155]
	v_mfma_f32_16x16x32_bf16 v[136:139], v[196:199], v[76:79], v[136:139]
	s_waitcnt lgkmcnt(4)
	v_mfma_f32_16x16x32_bf16 v[152:155], v[200:203], v[60:63], v[152:155]
	v_mfma_f32_16x16x32_bf16 v[136:139], v[200:203], v[80:83], v[136:139]
	s_waitcnt lgkmcnt(3)
	v_mfma_f32_16x16x32_bf16 v[148:151], v[204:207], v[68:71], v[148:151]
	s_waitcnt lgkmcnt(2)
	v_mfma_f32_16x16x32_bf16 v[148:151], v[208:211], v[72:75], v[148:151]
	s_waitcnt lgkmcnt(1)
	v_mfma_f32_16x16x32_bf16 v[148:151], v[212:215], v[76:79], v[148:151]
	s_waitcnt lgkmcnt(0)
	v_mfma_f32_16x16x32_bf16 v[148:151], v[246:249], v[80:83], v[148:151]

.LBB0_973:
	v_add_u32_e32 v216, s64, v229
	s_add_i32 s46, s60, s11
	s_and_b32 s46, s46, 3
	s_mul_i32 s46, s46, 0x8c00
	v_add_u32_e32 v217, s46, v230
	s_add_i32 s60, s60, s16
	s_and_b32 s46, s60, 3
	s_mul_i32 s46, s46, 0x8c00
	v_add_u32_e32 v236, s61, v229
	v_add_u32_e32 v237, s46, v231
	v_add_u32_e32 v80, s27, v233
	ds_read_b64_tr_b16 v[52:53], v216 offset:17408
	ds_read_b64_tr_b16 v[54:55], v216 offset:22016
	ds_read_b64_tr_b16 v[56:57], v217 offset:17408
	ds_read_b64_tr_b16 v[58:59], v217 offset:22016
	ds_read_b64_tr_b16 v[60:61], v216 offset:17472
	ds_read_b64_tr_b16 v[62:63], v216 offset:22080
	ds_read_b64_tr_b16 v[64:65], v217 offset:17472
	ds_read_b64_tr_b16 v[66:67], v217 offset:22080
	ds_read_b64_tr_b16 v[68:69], v216 offset:17504
	ds_read_b64_tr_b16 v[70:71], v216 offset:22112
	ds_read_b64_tr_b16 v[72:73], v217 offset:17504
	ds_read_b64_tr_b16 v[74:75], v217 offset:22112
	v_exp_f32_e32 v151, v167
	v_exp_f32_e32 v155, v184
	v_exp_f32_e32 v167, v100
	v_exp_f32_e32 v184, v101
	v_exp_f32_e32 v185, v102
	v_exp_f32_e32 v100, v144
	v_exp_f32_e32 v101, v145
	v_exp_f32_e32 v102, v146
	v_exp_f32_e32 v153, v153
	v_exp_f32_e32 v154, v154
	v_exp_f32_e32 v84, v84
	v_exp_f32_e32 v85, v85
	v_exp_f32_e32 v86, v86
	v_exp_f32_e32 v87, v87
	v_exp_f32_e32 v92, v92
	v_exp_f32_e32 v93, v93
	v_exp_f32_e32 v94, v94
	v_exp_f32_e32 v95, v95
	v_exp_f32_e32 v103, v103
	v_exp_f32_e32 v186, v108
	v_exp_f32_e32 v187, v109
	v_exp_f32_e32 v188, v110
	v_exp_f32_e32 v189, v111
	v_exp_f32_e32 v116, v116
	v_exp_f32_e32 v117, v117
	v_exp_f32_e32 v118, v118
	v_exp_f32_e32 v119, v119
	v_exp_f32_e32 v152, v152
	v_exp_f32_e32 v148, v148
	v_exp_f32_e32 v149, v149
	v_exp_f32_e32 v150, v150
	v_exp_f32_e32 v144, v147
	v_exp_f32_e32 v88, v88
	v_exp_f32_e32 v89, v89
	v_exp_f32_e32 v90, v90
	v_exp_f32_e32 v91, v91
	v_exp_f32_e32 v96, v96
	v_exp_f32_e32 v97, v97
	v_exp_f32_e32 v98, v98
	v_exp_f32_e32 v99, v99
	v_exp_f32_e32 v191, v112
	v_exp_f32_e32 v192, v113
	v_exp_f32_e32 v193, v114
	v_exp_f32_e32 v194, v115
	v_exp_f32_e32 v120, v120
	v_exp_f32_e32 v121, v121
	v_cvt_pk_bf16_f32 v108, v151, v155
	v_cvt_pk_bf16_f32 v109, v153, v154
	v_cvt_pk_bf16_f32 v110, v84, v85
	v_cvt_pk_bf16_f32 v111, v86, v87
	v_cvt_pk_bf16_f32 v112, v157, v157
	v_cvt_pk_bf16_f32 v113, v157, v157
	v_cvt_pk_bf16_f32 v114, v100, v101
	v_cvt_pk_bf16_f32 v115, v102, v144
	v_cvt_pk_bf16_f32 v100, v92, v93
	v_cvt_pk_bf16_f32 v101, v94, v95
	v_cvt_pk_bf16_f32 v102, v167, v184
	v_exp_f32_e32 v124, v124
	v_exp_f32_e32 v125, v125
	v_exp_f32_e32 v126, v126
	v_exp_f32_e32 v127, v127
	v_exp_f32_e32 v132, v132
	v_exp_f32_e32 v133, v133
	v_exp_f32_e32 v134, v134
	v_exp_f32_e32 v135, v135
	v_exp_f32_e32 v145, v104
	v_exp_f32_e32 v146, v105
	v_exp_f32_e32 v147, v106
	v_exp_f32_e32 v190, v107
	v_exp_f32_e32 v122, v122
	v_exp_f32_e32 v123, v123
	v_exp_f32_e32 v128, v128
	v_exp_f32_e32 v129, v129
	v_exp_f32_e32 v130, v130
	v_exp_f32_e32 v131, v131
	v_exp_f32_e32 v136, v136
	v_exp_f32_e32 v137, v137
	v_exp_f32_e32 v138, v138
	v_exp_f32_e32 v139, v139
	v_exp_f32_e32 v140, v140
	v_exp_f32_e32 v141, v141
	v_exp_f32_e32 v142, v142
	v_exp_f32_e32 v143, v143
	v_cvt_pk_bf16_f32 v103, v185, v103
	v_cvt_pk_bf16_f32 v104, v88, v89
	v_cvt_pk_bf16_f32 v105, v90, v91
	v_cvt_pk_bf16_f32 v106, v96, v97
	v_cvt_pk_bf16_f32 v107, v98, v99
	v_cvt_pk_bf16_f32 v92, v186, v187
	v_cvt_pk_bf16_f32 v93, v188, v189
	v_cvt_pk_bf16_f32 v94, v116, v117
	v_cvt_pk_bf16_f32 v95, v118, v119
	v_cvt_pk_bf16_f32 v96, v145, v146
	v_cvt_pk_bf16_f32 v97, v147, v190
	v_cvt_pk_bf16_f32 v98, v191, v192
	v_cvt_pk_bf16_f32 v99, v193, v194
	v_cvt_pk_bf16_f32 v84, v124, v125
	v_cvt_pk_bf16_f32 v85, v126, v127
	v_cvt_pk_bf16_f32 v86, v132, v133
	v_cvt_pk_bf16_f32 v87, v134, v135
	v_cvt_pk_bf16_f32 v88, v120, v121
	v_cvt_pk_bf16_f32 v89, v122, v123
	v_cvt_pk_bf16_f32 v90, v128, v129
	v_cvt_pk_bf16_f32 v91, v130, v131
	v_cvt_pk_bf16_f32 v148, v152, v148
	v_cvt_pk_bf16_f32 v149, v149, v150
	v_cvt_pk_bf16_f32 v150, v157, v157
	v_cvt_pk_bf16_f32 v151, v157, v157
	v_cvt_pk_bf16_f32 v152, v136, v137
	v_cvt_pk_bf16_f32 v153, v138, v139
	v_cvt_pk_bf16_f32 v154, v140, v141
	v_cvt_pk_bf16_f32 v155, v142, v143
	s_waitcnt lgkmcnt(10)
	v_mfma_f32_16x16x32_bf16 v[124:127], v[52:55], v[108:111], 0
	ds_read_b64_tr_b16 v[76:77], v216 offset:17536
	ds_read_b64_tr_b16 v[78:79], v216 offset:22144
	v_mfma_f32_16x16x32_bf16 v[116:119], v[52:55], v[112:115], 0
	s_mov_b64 s[96:97], s[62:63]
	s_waitcnt lgkmcnt(10)
	v_mfma_f32_16x16x32_bf16 v[124:127], v[56:59], v[100:103], v[124:127]
	ds_read_b64_tr_b16 v[52:53], v217 offset:17536
	ds_read_b64_tr_b16 v[54:55], v217 offset:22144
	v_mfma_f32_16x16x32_bf16 v[116:119], v[56:59], v[104:107], v[116:119]
	s_waitcnt lgkmcnt(10)
	v_mfma_f32_16x16x32_bf16 v[136:139], v[60:63], v[108:111], 0
	ds_read_b64_tr_b16 v[56:57], v216 offset:17568
	ds_read_b64_tr_b16 v[58:59], v216 offset:22176
	v_mfma_f32_16x16x32_bf16 v[132:135], v[60:63], v[112:115], 0
	s_waitcnt lgkmcnt(10)
	v_mfma_f32_16x16x32_bf16 v[136:139], v[64:67], v[100:103], v[136:139]
	ds_read_b64_tr_b16 v[60:61], v217 offset:17568
	ds_read_b64_tr_b16 v[62:63], v217 offset:22176
	v_mfma_f32_16x16x32_bf16 v[132:135], v[64:67], v[104:107], v[132:135]
	s_waitcnt lgkmcnt(10)
	v_mfma_f32_16x16x32_bf16 v[144:147], v[68:71], v[108:111], 0
	ds_read_b64_tr_b16 v[64:65], v216 offset:17600
	ds_read_b64_tr_b16 v[66:67], v216 offset:22208
	v_mfma_f32_16x16x32_bf16 v[140:143], v[68:71], v[112:115], 0
	s_waitcnt lgkmcnt(10)
	v_mfma_f32_16x16x32_bf16 v[144:147], v[72:75], v[100:103], v[144:147]
	ds_read_b64_tr_b16 v[68:69], v217 offset:17600
	ds_read_b64_tr_b16 v[70:71], v217 offset:22208
	v_mfma_f32_16x16x32_bf16 v[140:143], v[72:75], v[104:107], v[140:143]
	s_waitcnt lgkmcnt(10)
	v_mfma_f32_16x16x32_bf16 v[188:191], v[76:79], v[108:111], 0
	ds_read_b64_tr_b16 v[72:73], v216 offset:17440
	ds_read_b64_tr_b16 v[74:75], v216 offset:22048
	v_mfma_f32_16x16x32_bf16 v[184:187], v[76:79], v[112:115], 0
	s_waitcnt lgkmcnt(10)
	v_mfma_f32_16x16x32_bf16 v[188:191], v[52:55], v[100:103], v[188:191]
	ds_read_b64_tr_b16 v[76:77], v216 offset:17632
	ds_read_b64_tr_b16 v[78:79], v216 offset:22240
	v_mfma_f32_16x16x32_bf16 v[184:187], v[52:55], v[104:107], v[184:187]
	s_waitcnt lgkmcnt(10)
	v_mfma_f32_16x16x32_bf16 v[196:199], v[56:59], v[108:111], 0
	ds_read_b64_tr_b16 v[52:53], v217 offset:17440
	ds_read_b64_tr_b16 v[54:55], v217 offset:22048
	v_mfma_f32_16x16x32_bf16 v[192:195], v[56:59], v[112:115], 0
	s_waitcnt lgkmcnt(10)
	v_mfma_f32_16x16x32_bf16 v[196:199], v[60:63], v[100:103], v[196:199]
	ds_read_b64_tr_b16 v[56:57], v217 offset:17632
	ds_read_b64_tr_b16 v[58:59], v217 offset:22240
	v_mfma_f32_16x16x32_bf16 v[192:195], v[60:63], v[104:107], v[192:195]
	s_waitcnt lgkmcnt(10)
	v_mfma_f32_16x16x32_bf16 v[204:207], v[64:67], v[108:111], 0
	ds_read_b64_tr_b16 v[60:61], v236 offset:17408
	ds_read_b64_tr_b16 v[62:63], v236 offset:22016
	v_mfma_f32_16x16x32_bf16 v[200:203], v[64:67], v[112:115], 0
	s_waitcnt lgkmcnt(10)
	v_mfma_f32_16x16x32_bf16 v[204:207], v[68:71], v[100:103], v[204:207]
	ds_read_b64_tr_b16 v[64:65], v236 offset:17440
	ds_read_b64_tr_b16 v[66:67], v236 offset:22048
	v_mfma_f32_16x16x32_bf16 v[200:203], v[68:71], v[104:107], v[200:203]
	s_mov_b64 s[60:61], -1
	s_waitcnt lgkmcnt(10)
	v_mfma_f32_16x16x32_bf16 v[128:131], v[72:75], v[108:111], 0
	ds_read_b64_tr_b16 v[68:69], v236 offset:17472
	ds_read_b64_tr_b16 v[70:71], v236 offset:22080
	v_mfma_f32_16x16x32_bf16 v[120:123], v[72:75], v[112:115], 0
	s_waitcnt lgkmcnt(10)
	v_mfma_f32_16x16x32_bf16 v[212:215], v[76:79], v[108:111], 0
	ds_read_b64_tr_b16 v[72:73], v236 offset:17504
	ds_read_b64_tr_b16 v[74:75], v236 offset:22112
	v_mfma_f32_16x16x32_bf16 v[208:211], v[76:79], v[112:115], 0
	v_mfma_f32_16x16x32_bf16 v[108:111], v[0:3], v[108:111], 0
	v_mfma_f32_16x16x32_bf16 v[112:115], v[0:3], v[112:115], 0
	s_waitcnt lgkmcnt(10)
	v_mfma_f32_16x16x32_bf16 v[128:131], v[52:55], v[100:103], v[128:131]
	ds_read_b64_tr_b16 v[76:77], v236 offset:17536
	ds_read_b64_tr_b16 v[78:79], v236 offset:22144
	v_mfma_f32_16x16x32_bf16 v[120:123], v[52:55], v[104:107], v[120:123]
	s_waitcnt lgkmcnt(10)
	v_mfma_f32_16x16x32_bf16 v[212:215], v[56:59], v[100:103], v[212:215]
	ds_read_b64_tr_b16 v[52:53], v236 offset:17568
	ds_read_b64_tr_b16 v[54:55], v236 offset:22176
	v_mfma_f32_16x16x32_bf16 v[208:211], v[56:59], v[104:107], v[208:211]
	v_mfma_f32_16x16x32_bf16 v[100:103], v[0:3], v[100:103], v[108:111]
	v_mfma_f32_16x16x32_bf16 v[104:107], v[0:3], v[104:107], v[112:115]
	s_nop 1
	s_waitcnt lgkmcnt(10)
	v_mfma_f32_16x16x32_bf16 v[124:127], v[60:63], v[92:95], v[124:127]
	ds_read_b64_tr_b16 v[56:57], v236 offset:17600
	ds_read_b64_tr_b16 v[58:59], v236 offset:22208
	v_mfma_f32_16x16x32_bf16 v[108:111], v[60:63], v[96:99], v[116:119]
	s_waitcnt lgkmcnt(10)
	v_mfma_f32_16x16x32_bf16 v[116:119], v[64:67], v[92:95], v[128:131]
	ds_read_b64_tr_b16 v[60:61], v236 offset:17632
	ds_read_b64_tr_b16 v[62:63], v236 offset:22240
	v_mfma_f32_16x16x32_bf16 v[112:115], v[64:67], v[96:99], v[120:123]
	s_nop 2
	s_waitcnt lgkmcnt(10)
	v_mfma_f32_16x16x32_bf16 v[128:131], v[68:71], v[92:95], v[136:139]
	ds_read_b64_tr_b16 v[64:65], v237 offset:17408
	ds_read_b64_tr_b16 v[66:67], v237 offset:22016
	v_mfma_f32_16x16x32_bf16 v[120:123], v[68:71], v[96:99], v[132:135]
	s_nop 2
	s_waitcnt lgkmcnt(10)
	v_mfma_f32_16x16x32_bf16 v[136:139], v[72:75], v[92:95], v[144:147]
	ds_read_b64_tr_b16 v[68:69], v237 offset:17440
	ds_read_b64_tr_b16 v[70:71], v237 offset:22048
	v_mfma_f32_16x16x32_bf16 v[132:135], v[72:75], v[96:99], v[140:143]
	s_nop 2
	s_waitcnt lgkmcnt(10)
	v_mfma_f32_16x16x32_bf16 v[144:147], v[76:79], v[92:95], v[188:191]
	ds_read_b64_tr_b16 v[72:73], v237 offset:17504
	ds_read_b64_tr_b16 v[74:75], v237 offset:22112
	v_mfma_f32_16x16x32_bf16 v[140:143], v[76:79], v[96:99], v[184:187]
	s_nop 2
	s_waitcnt lgkmcnt(10)
	v_mfma_f32_16x16x32_bf16 v[188:191], v[52:55], v[92:95], v[196:199]
	ds_read_b64_tr_b16 v[76:77], v237 offset:17536
	ds_read_b64_tr_b16 v[78:79], v237 offset:22144
	v_mfma_f32_16x16x32_bf16 v[184:187], v[52:55], v[96:99], v[192:195]
	s_nop 2
	s_waitcnt lgkmcnt(10)
	v_mfma_f32_16x16x32_bf16 v[196:199], v[56:59], v[92:95], v[204:207]
	ds_read_b64_tr_b16 v[52:53], v237 offset:17568
	ds_read_b64_tr_b16 v[54:55], v237 offset:22176
	v_mfma_f32_16x16x32_bf16 v[192:195], v[56:59], v[96:99], v[200:203]
	s_nop 2
	s_waitcnt lgkmcnt(10)
	v_mfma_f32_16x16x32_bf16 v[204:207], v[60:63], v[92:95], v[212:215]
	ds_read_b64_tr_b16 v[56:57], v237 offset:17600
	ds_read_b64_tr_b16 v[58:59], v237 offset:22208
	v_mfma_f32_16x16x32_bf16 v[200:203], v[60:63], v[96:99], v[208:211]
	v_mfma_f32_16x16x32_bf16 v[92:95], v[0:3], v[92:95], v[100:103]
	v_mfma_f32_16x16x32_bf16 v[96:99], v[0:3], v[96:99], v[104:107]
	s_nop 1
	s_waitcnt lgkmcnt(10)
	v_mfma_f32_16x16x32_bf16 v[124:127], v[64:67], v[84:87], v[124:127]
	ds_read_b64_tr_b16 v[60:61], v237 offset:17472
	ds_read_b64_tr_b16 v[62:63], v237 offset:22080
	v_mfma_f32_16x16x32_bf16 v[100:103], v[64:67], v[88:91], v[108:111]
	s_waitcnt lgkmcnt(10)
	v_mfma_f32_16x16x32_bf16 v[108:111], v[68:71], v[84:87], v[116:119]
	ds_read_b64_tr_b16 v[64:65], v237 offset:17632
	ds_read_b64_tr_b16 v[66:67], v237 offset:22240
	v_mfma_f32_16x16x32_bf16 v[104:107], v[68:71], v[88:91], v[112:115]
	s_nop 2
	s_waitcnt lgkmcnt(10)
	v_mfma_f32_16x16x32_bf16 v[136:139], v[72:75], v[84:87], v[136:139]
	ds_read_b64_tr_b16 v[68:69], v80 offset:17408
	ds_read_b64_tr_b16 v[70:71], v80 offset:22016
	v_mfma_f32_16x16x32_bf16 v[208:211], v[72:75], v[88:91], v[132:135]
	s_waitcnt lgkmcnt(10)
	v_mfma_f32_16x16x32_bf16 v[144:147], v[76:79], v[84:87], v[144:147]
	ds_read_b64_tr_b16 v[72:73], v80 offset:17440
	ds_read_b64_tr_b16 v[74:75], v80 offset:22048
	v_mfma_f32_16x16x32_bf16 v[140:143], v[76:79], v[88:91], v[140:143]
	s_waitcnt lgkmcnt(10)
	v_mfma_f32_16x16x32_bf16 v[188:191], v[52:55], v[84:87], v[188:191]
	ds_read_b64_tr_b16 v[76:77], v80 offset:17472
	ds_read_b64_tr_b16 v[78:79], v80 offset:22080
	v_mfma_f32_16x16x32_bf16 v[184:187], v[52:55], v[88:91], v[184:187]
	s_waitcnt lgkmcnt(10)
	v_mfma_f32_16x16x32_bf16 v[196:199], v[56:59], v[84:87], v[196:199]
	ds_read_b64_tr_b16 v[52:53], v80 offset:17504
	ds_read_b64_tr_b16 v[54:55], v80 offset:22112
	v_mfma_f32_16x16x32_bf16 v[192:195], v[56:59], v[88:91], v[192:195]
	s_waitcnt lgkmcnt(10)
	v_mfma_f32_16x16x32_bf16 v[128:131], v[60:63], v[84:87], v[128:131]
	ds_read_b64_tr_b16 v[56:57], v80 offset:17536
	ds_read_b64_tr_b16 v[58:59], v80 offset:22144
	s_waitcnt lgkmcnt(10)
	v_mfma_f32_16x16x32_bf16 v[204:207], v[64:67], v[84:87], v[204:207]
	v_mfma_f32_16x16x32_bf16 v[212:215], v[0:3], v[84:87], v[92:95]
	s_nop 0
	v_mfma_f32_16x16x32_bf16 v[112:115], v[60:63], v[88:91], v[120:123]
	ds_read_b64_tr_b16 v[60:61], v80 offset:17568
	ds_read_b64_tr_b16 v[62:63], v80 offset:22176
	v_mfma_f32_16x16x32_bf16 v[200:203], v[64:67], v[88:91], v[200:203]
	v_mfma_f32_16x16x32_bf16 v[246:249], v[0:3], v[88:91], v[96:99]
	s_waitcnt lgkmcnt(10)
	v_mfma_f32_16x16x32_bf16 v[120:123], v[68:71], v[148:151], v[124:127]
	ds_read_b64_tr_b16 v[64:65], v80 offset:17600
	ds_read_b64_tr_b16 v[66:67], v80 offset:22208
	v_mfma_f32_16x16x32_bf16 v[88:91], v[68:71], v[152:155], v[100:103]
	s_waitcnt lgkmcnt(10)
	v_mfma_f32_16x16x32_bf16 v[116:119], v[72:75], v[148:151], v[108:111]
	ds_read_b64_tr_b16 v[68:69], v80 offset:17632
	ds_read_b64_tr_b16 v[70:71], v80 offset:22240
	v_mfma_f32_16x16x32_bf16 v[84:87], v[72:75], v[152:155], v[104:107]
	s_waitcnt lgkmcnt(10)
	v_mfma_f32_16x16x32_bf16 v[124:127], v[76:79], v[148:151], v[128:131]
	v_mfma_f32_16x16x32_bf16 v[92:95], v[76:79], v[152:155], v[112:115]
	s_waitcnt lgkmcnt(8)
	v_mfma_f32_16x16x32_bf16 v[132:135], v[52:55], v[148:151], v[136:139]
	v_mfma_f32_16x16x32_bf16 v[100:103], v[52:55], v[152:155], v[208:211]
	s_waitcnt lgkmcnt(6)
	v_mfma_f32_16x16x32_bf16 v[128:131], v[56:59], v[148:151], v[144:147]
	s_add_u32 s46, s96, 0x700000
	s_addc_u32 s47, s97, 0
	v_mfma_f32_16x16x32_bf16 v[96:99], v[56:59], v[152:155], v[140:143]
	s_andn2_b64 vcc, exec, s[90:91]
	s_waitcnt lgkmcnt(4)
	v_mfma_f32_16x16x32_bf16 v[136:139], v[60:63], v[148:151], v[188:191]
	s_waitcnt lgkmcnt(2)
	v_mfma_f32_16x16x32_bf16 v[140:143], v[64:67], v[148:151], v[196:199]
	s_waitcnt lgkmcnt(0)
	v_mfma_f32_16x16x32_bf16 v[144:147], v[68:71], v[148:151], v[204:207]
	v_mfma_f32_16x16x32_bf16 v[148:151], v[0:3], v[148:151], v[212:215]
	v_mfma_f32_16x16x32_bf16 v[104:107], v[60:63], v[152:155], v[184:187]
	v_mfma_f32_16x16x32_bf16 v[108:111], v[64:67], v[152:155], v[192:195]
	s_nop 5
	v_max_f32_e32 v148, v148, v148
	v_mfma_f32_16x16x32_bf16 v[112:115], v[68:71], v[152:155], v[200:203]
	v_mfma_f32_16x16x32_bf16 v[150:153], v[0:3], v[152:155], v[246:249]
	s_nop 2
	v_max_f32_e32 v246, 0xda24260, v148
	s_nop 3
	v_max_f32_e32 v148, v150, v150
	v_max_f32_e32 v167, 0xda24260, v148
	v_lshlrev_b64 v[150:151], s23, v[182:183]
	v_lshl_add_u64 v[148:149], v[176:177], 0, s[92:93]
	s_cbranch_vccz .LBB0_976
	s_andn2_b64 vcc, exec, s[60:61]
	s_cbranch_vccz .LBB0_977
